# v16: v13 + P0 gate/up weight slabs: all 16 loads of a batch issued before the first wait (was 2 loads + vmcnt(0) + 14 loads: one extra exposed HBM round trip per batch)
# speedup vs baseline: 1.0063x; 1.0063x over previous
.LBB0_28:
	s_and_b64 vcc, exec, s[28:29]
	s_cbranch_vccz .LBB0_21
	s_cmpk_gt_i32 s62, 0x157
	s_cselect_b64 s[28:29], -1, 0
	s_and_b64 s[30:31], s[28:29], exec
	s_cselect_b32 s68, 0xfffffea8, 0
	s_cselect_b32 s37, s11, s9
	s_cselect_b32 s36, s10, s8
	s_add_i32 s68, s68, s62
	s_lshl_b32 s30, s68, 5
	v_lshl_add_u64 v[0:1], s[36:37], 0, v[72:73]
	s_ashr_i32 s31, s30, 31
	v_lshl_add_u64 v[0:1], s[30:31], 2, v[0:1]
	v_lshlrev_b32_e32 v66, 2, v64
	v_lshl_add_u64 v[56:57], v[0:1], 0, v[66:67]
	s_mov_b32 s31, 0xa000
	v_add_co_u32_e32 v58, vcc, s31, v56
	s_mov_b32 s31, 0x15000
	s_nop 0
	v_addc_co_u32_e32 v59, vcc, 0, v57, vcc
	v_add_co_u32_e32 v0, vcc, s31, v56
	s_mov_b32 s31, 0x20000
	s_nop 0
	v_addc_co_u32_e32 v1, vcc, 0, v57, vcc
	v_add_co_u32_e32 v2, vcc, s31, v56
	s_mov_b32 s31, 0x2b000
	s_nop 0
	v_addc_co_u32_e32 v3, vcc, 0, v57, vcc
	global_load_dwordx4 v[48:51], v[0:1], off offset:2048 nt
	global_load_dwordx4 v[52:55], v[2:3], off offset:1024 nt
	v_add_co_u32_e32 v0, vcc, s31, v56
	s_mov_b32 s31, 0x35000
	s_nop 0
	v_addc_co_u32_e32 v1, vcc, 0, v57, vcc
	v_add_co_u32_e32 v2, vcc, s31, v56
	s_mov_b32 s31, 0x40000
	s_nop 0
	v_addc_co_u32_e32 v3, vcc, 0, v57, vcc
	global_load_dwordx4 v[36:39], v[0:1], off nt
	global_load_dwordx4 v[40:43], v[2:3], off offset:3072 nt
	v_add_co_u32_e32 v0, vcc, s31, v56
	s_mov_b32 s31, 0x4b000
	s_nop 0
	v_addc_co_u32_e32 v1, vcc, 0, v57, vcc
	v_add_co_u32_e32 v2, vcc, s31, v56
	s_mov_b32 s31, 0x56000
	s_nop 0
	v_addc_co_u32_e32 v3, vcc, 0, v57, vcc
	global_load_dwordx4 v[44:47], v[0:1], off offset:2048 nt
	global_load_dwordx4 v[32:35], v[2:3], off offset:1024 nt
	v_add_co_u32_e32 v0, vcc, s31, v56
	s_mov_b32 s31, 0x60000
	s_nop 0
	v_addc_co_u32_e32 v1, vcc, 0, v57, vcc
	v_add_co_u32_e32 v2, vcc, s31, v56
	s_mov_b32 s31, 0x6b000
	s_nop 0
	v_addc_co_u32_e32 v3, vcc, 0, v57, vcc
	global_load_dwordx4 v[28:31], v[0:1], off nt
	global_load_dwordx4 v[24:27], v[2:3], off offset:3072 nt
	v_add_co_u32_e32 v0, vcc, s31, v56
	s_mov_b32 s31, 0x76000
	s_nop 0
	v_addc_co_u32_e32 v1, vcc, 0, v57, vcc
	v_add_co_u32_e32 v2, vcc, s31, v56
	s_mov_b32 s31, 0x81000
	s_nop 0
	v_addc_co_u32_e32 v3, vcc, 0, v57, vcc
	global_load_dwordx4 v[20:23], v[0:1], off offset:2048 nt
	global_load_dwordx4 v[16:19], v[2:3], off offset:1024 nt
	v_add_co_u32_e32 v0, vcc, s31, v56
	s_mov_b32 s31, 0x8b000
	s_nop 0
	v_addc_co_u32_e32 v1, vcc, 0, v57, vcc
	v_add_co_u32_e32 v2, vcc, s31, v56
	s_mov_b32 s31, 0x96000
	s_nop 0
	v_addc_co_u32_e32 v3, vcc, 0, v57, vcc
	global_load_dwordx4 v[12:15], v[0:1], off nt
	global_load_dwordx4 v[8:11], v[2:3], off offset:3072 nt
	v_add_co_u32_e32 v0, vcc, s31, v56
	s_mov_b32 s31, 0xa1000
	s_nop 0
	v_addc_co_u32_e32 v1, vcc, 0, v57, vcc
	v_add_co_u32_e32 v2, vcc, s31, v56
	s_mov_b32 s31, 0xac000
	s_nop 0
	v_addc_co_u32_e32 v3, vcc, 0, v57, vcc
	global_load_dwordx4 v[4:7], v[0:1], off offset:2048 nt
	s_nop 0
	global_load_dwordx4 v[0:3], v[2:3], off offset:1024 nt
	s_nop 0
	global_load_dwordx4 v[90:93], v[58:59], off offset:3072 nt
	global_load_dwordx4 v[94:97], v[56:57], off nt
	s_waitcnt vmcnt(0)
	v_cvt_pk_bf16_f32 v60, v94, v95
	v_max3_f32 v62, |v94|, 0, |v90|
	v_max3_f32 v63, |v95|, 0, |v91|
	v_max3_f32 v66, |v96|, 0, |v92|
	v_max3_f32 v79, |v97|, 0, |v93|
	v_max3_f32 v81, v62, |v48|, |v52|
	v_cvt_pk_bf16_f32 v58, v96, v97
	v_cvt_pk_bf16_f32 v61, v90, v91
	v_cvt_pk_bf16_f32 v59, v92, v93
	v_max3_f32 v63, v63, |v49|, |v53|
	v_max3_f32 v66, v66, |v50|, |v54|
	v_max3_f32 v79, v79, |v51|, |v55|
	v_cvt_pk_bf16_f32 v62, v48, v49
	v_cvt_pk_bf16_f32 v48, v50, v51
	v_cvt_pk_bf16_f32 v50, v52, v53
	v_max3_f32 v52, v81, |v36|, |v40|
	v_cvt_pk_bf16_f32 v49, v54, v55
	v_max3_f32 v53, v63, |v37|, |v41|
	v_max3_f32 v54, v66, |v38|, |v42|
	v_max3_f32 v55, v79, |v39|, |v43|
	v_cvt_pk_bf16_f32 v51, v36, v37
	v_cvt_pk_bf16_f32 v36, v38, v39
	v_cvt_pk_bf16_f32 v39, v40, v41
	v_cvt_pk_bf16_f32 v37, v42, v43
	v_max3_f32 v42, v52, |v44|, |v32|
	v_cvt_pk_bf16_f32 v40, v44, v45
	v_cvt_pk_bf16_f32 v38, v46, v47
	v_max3_f32 v43, v53, |v45|, |v33|
	v_max3_f32 v44, v54, |v46|, |v34|
	v_max3_f32 v45, v55, |v47|, |v35|
	v_cvt_pk_bf16_f32 v41, v32, v33
	v_cvt_pk_bf16_f32 v32, v34, v35
	v_cvt_pk_bf16_f32 v34, v28, v29
	v_max3_f32 v28, v42, |v28|, |v24|
	v_cvt_pk_bf16_f32 v33, v30, v31
	v_max3_f32 v29, v43, |v29|, |v25|
	v_max3_f32 v42, v45, |v31|, |v27|
	v_cvt_pk_bf16_f32 v31, v24, v25
	v_cvt_pk_bf16_f32 v24, v26, v27
	v_cvt_pk_bf16_f32 v35, v20, v21
	v_max3_f32 v20, v28, |v20|, |v16|
	v_max3_f32 v30, v44, |v30|, |v26|
	v_cvt_pk_bf16_f32 v25, v22, v23
	v_max3_f32 v21, v29, |v21|, |v17|
	v_cvt_pk_bf16_f32 v44, v16, v17
	v_cvt_pk_bf16_f32 v16, v18, v19
	v_cvt_pk_bf16_f32 v45, v12, v13
	v_max3_f32 v12, v20, |v12|, |v8|
	v_max3_f32 v22, v30, |v22|, |v18|
	v_max3_f32 v23, v42, |v23|, |v19|
	v_cvt_pk_bf16_f32 v17, v14, v15
	v_max3_f32 v13, v21, |v13|, |v9|
	v_cvt_pk_bf16_f32 v52, v8, v9
	v_cvt_pk_bf16_f32 v18, v10, v11
	v_cvt_pk_bf16_f32 v53, v4, v5
	v_cvt_pk_bf16_f32 v19, v6, v7
	v_max3_f32 v21, v12, |v4|, |v0|
	v_cvt_pk_bf16_f32 v63, v0, v1
	v_add_co_u32_e32 v0, vcc, s31, v56
	v_max3_f32 v14, v22, |v14|, |v10|
	v_max3_f32 v26, v13, |v5|, |v1|
	v_addc_co_u32_e32 v1, vcc, 0, v57, vcc
	s_mov_b32 s31, 0xb6000
	v_max3_f32 v15, v23, |v15|, |v11|
	v_max3_f32 v27, v14, |v6|, |v2|
	v_cvt_pk_bf16_f32 v20, v2, v3
	v_add_co_u32_e32 v2, vcc, s31, v56
	v_max3_f32 v28, v15, |v7|, |v3|
	s_nop 0
	v_addc_co_u32_e32 v3, vcc, 0, v57, vcc
	global_load_dwordx4 v[8:11], v[0:1], off nt
	global_load_dwordx4 v[12:15], v[2:3], off offset:3072 nt
	v_add_co_u32_e32 v4, vcc, s49, v56
	v_addc_co_u32_e32 v5, vcc, 0, v57, vcc
	v_add_co_u32_e32 v6, vcc, s50, v56
	s_nop 0
	v_addc_co_u32_e32 v7, vcc, 0, v57, vcc
	v_add_co_u32_e32 v22, vcc, s51, v56
	s_nop 0
	v_addc_co_u32_e32 v23, vcc, 0, v57, vcc
	v_add_co_u32_e32 v42, vcc, s52, v56
	s_nop 0
	v_addc_co_u32_e32 v43, vcc, 0, v57, vcc
	v_add_co_u32_e32 v46, vcc, s53, v56
	s_nop 1
	v_addc_co_u32_e32 v47, vcc, 0, v57, vcc
	v_add_co_u32_e32 v54, vcc, s54, v56
	s_nop 1
	v_addc_co_u32_e32 v55, vcc, 0, v57, vcc
	v_add_co_u32_e32 v82, vcc, s55, v56
	s_nop 1
	v_addc_co_u32_e32 v83, vcc, 0, v57, vcc
	v_add_co_u32_e32 v114, vcc, s56, v56
	s_nop 1
	v_addc_co_u32_e32 v115, vcc, 0, v57, vcc
	v_add_co_u32_e32 v118, vcc, s57, v56
	s_nop 1
	v_addc_co_u32_e32 v119, vcc, 0, v57, vcc
	v_add_co_u32_e32 v122, vcc, s58, v56
	s_nop 1
	v_addc_co_u32_e32 v123, vcc, 0, v57, vcc
	v_add_co_u32_e32 v126, vcc, s59, v56
	s_nop 1
	v_addc_co_u32_e32 v127, vcc, 0, v57, vcc
	v_add_co_u32_e32 v134, vcc, s60, v56
	s_nop 1
	v_addc_co_u32_e32 v135, vcc, 0, v57, vcc
	v_add_co_u32_e32 v138, vcc, s61, v56
	s_nop 1
	v_addc_co_u32_e32 v139, vcc, 0, v57, vcc
	v_add_co_u32_e32 v140, vcc, s67, v56
	s_nop 1
	v_addc_co_u32_e32 v141, vcc, 0, v57, vcc
	v_mov_b32_e32 v206, v26
	v_mov_b32_e32 v207, v27
	v_mov_b32_e32 v208, v28
	global_load_dwordx4 v[26:29], v[4:5], off offset:2048 nt
	global_load_dwordx4 v[90:93], v[6:7], off offset:1024 nt
	global_load_dwordx4 v[94:97], v[22:23], off nt
	global_load_dwordx4 v[98:101], v[42:43], off offset:3072 nt
	global_load_dwordx4 v[102:105], v[46:47], off offset:2048 nt
	global_load_dwordx4 v[106:109], v[54:55], off offset:1024 nt
	global_load_dwordx4 v[110:113], v[82:83], off nt
	s_nop 0
	global_load_dwordx4 v[114:117], v[114:115], off offset:3072 nt
	s_nop 0
	global_load_dwordx4 v[118:121], v[118:119], off offset:2048 nt
	s_nop 0
	global_load_dwordx4 v[122:125], v[122:123], off offset:1024 nt
	s_nop 0
	global_load_dwordx4 v[130:133], v[126:127], off nt
	s_nop 0
	global_load_dwordx4 v[134:137], v[134:135], off offset:3072 nt
	s_nop 0
	global_load_dwordx4 v[0:3], v[138:139], off offset:2048 nt
	global_load_dwordx4 v[4:7], v[140:141], off offset:1024 nt
	s_waitcnt vmcnt(14)
	v_max3_f32 v66, v206, |v9|, |v13|
	v_max3_f32 v79, v207, |v10|, |v14|
	v_max3_f32 v129, v208, |v11|, |v15|
	v_max3_f32 v30, v21, |v8|, |v12|
	v_cvt_pk_bf16_f32 v81, v8, v9
	v_cvt_pk_bf16_f32 v21, v10, v11
	v_cvt_pk_bf16_f32 v82, v12, v13
	v_cvt_pk_bf16_f32 v22, v14, v15
	s_waitcnt vmcnt(13)
	v_cvt_pk_bf16_f32 v83, v26, v27
	s_waitcnt vmcnt(12)
	v_max3_f32 v8, v30, |v26|, |v90|
	v_max3_f32 v9, v66, |v27|, |v91|
	s_waitcnt vmcnt(10)
	v_max3_f32 v8, v8, |v94|, |v98|
	v_max3_f32 v10, v79, |v28|, |v92|
	v_max3_f32 v9, v9, |v95|, |v99|
	s_waitcnt vmcnt(8)
	v_max3_f32 v8, v8, |v102|, |v106|
	v_max3_f32 v11, v129, |v29|, |v93|
	v_max3_f32 v10, v10, |v96|, |v100|
	v_max3_f32 v9, v9, |v103|, |v107|
	s_waitcnt vmcnt(6)
	v_max3_f32 v8, v8, |v110|, |v114|
	v_max3_f32 v11, v11, |v97|, |v101|
	v_max3_f32 v10, v10, |v104|, |v108|
	v_max3_f32 v9, v9, |v111|, |v115|
	s_waitcnt vmcnt(4)
	v_max3_f32 v8, v8, |v118|, |v122|
	v_max3_f32 v11, v11, |v105|, |v109|
	v_max3_f32 v10, v10, |v112|, |v116|
	v_max3_f32 v9, v9, |v119|, |v123|
	s_waitcnt vmcnt(2)
	v_max3_f32 v8, v8, |v130|, |v134|
	v_cvt_pk_bf16_f32 v23, v28, v29
	v_cvt_pk_bf16_f32 v90, v90, v91
	v_cvt_pk_bf16_f32 v26, v92, v93
	v_cvt_pk_bf16_f32 v91, v94, v95
	v_cvt_pk_bf16_f32 v27, v96, v97
	v_cvt_pk_bf16_f32 v92, v98, v99
	v_cvt_pk_bf16_f32 v28, v100, v101
	v_cvt_pk_bf16_f32 v95, v102, v103
	v_cvt_pk_bf16_f32 v29, v104, v105
	v_cvt_pk_bf16_f32 v96, v106, v107
	v_cvt_pk_bf16_f32 v30, v108, v109
	v_max3_f32 v11, v11, |v113|, |v117|
	v_cvt_pk_bf16_f32 v99, v110, v111
	v_cvt_pk_bf16_f32 v42, v112, v113
	v_cvt_pk_bf16_f32 v100, v114, v115
	v_cvt_pk_bf16_f32 v43, v116, v117
	v_max3_f32 v10, v10, |v120|, |v124|
	v_cvt_pk_bf16_f32 v103, v118, v119
	v_cvt_pk_bf16_f32 v46, v120, v121
	v_cvt_pk_bf16_f32 v104, v122, v123
	v_cvt_pk_bf16_f32 v47, v124, v125
	v_max3_f32 v9, v9, |v131|, |v135|
	v_cvt_pk_bf16_f32 v107, v130, v131
	v_cvt_pk_bf16_f32 v54, v132, v133
	v_cvt_pk_bf16_f32 v108, v134, v135
	v_cvt_pk_bf16_f32 v55, v136, v137
	s_waitcnt vmcnt(0)
	v_max3_f32 v93, v8, |v0|, |v4|
	v_cvt_pk_bf16_f32 v111, v0, v1
	v_add_co_u32_e32 v0, vcc, s69, v56
	v_max3_f32 v11, v11, |v121|, |v125|
	v_max3_f32 v10, v10, |v132|, |v136|
	v_max3_f32 v94, v9, |v1|, |v5|
	v_addc_co_u32_e32 v1, vcc, 0, v57, vcc
	v_max3_f32 v11, v11, |v133|, |v137|
	v_max3_f32 v97, v10, |v2|, |v6|
	v_cvt_pk_bf16_f32 v66, v2, v3
	v_add_co_u32_e32 v2, vcc, s70, v56
	v_max3_f32 v98, v11, |v3|, |v7|
	s_nop 0
	v_addc_co_u32_e32 v3, vcc, 0, v57, vcc
	v_cvt_pk_bf16_f32 v112, v4, v5
	v_add_co_u32_e32 v4, vcc, s71, v56
	v_cvt_pk_bf16_f32 v79, v6, v7
	global_load_dwordx4 v[114:117], v[0:1], off nt
	global_load_dwordx4 v[118:121], v[2:3], off offset:3072 nt
	v_addc_co_u32_e32 v5, vcc, 0, v57, vcc
	v_add_co_u32_e32 v6, vcc, s72, v56
	v_addc_co_u32_e32 v7, vcc, 0, v57, vcc
	v_add_co_u32_e32 v8, vcc, s73, v56
	s_nop 0
	v_addc_co_u32_e32 v9, vcc, 0, v57, vcc
	v_add_co_u32_e32 v10, vcc, s74, v56
	s_nop 0
	v_addc_co_u32_e32 v11, vcc, 0, v57, vcc
	v_add_co_u32_e32 v12, vcc, s75, v56
	s_nop 0
	v_addc_co_u32_e32 v13, vcc, 0, v57, vcc
	v_add_co_u32_e32 v14, vcc, s76, v56
	s_nop 1
	v_addc_co_u32_e32 v15, vcc, 0, v57, vcc
	v_add_co_u32_e32 v126, vcc, s77, v56
	s_nop 1
	v_addc_co_u32_e32 v127, vcc, 0, v57, vcc
	v_add_co_u32_e32 v154, vcc, s78, v56
	s_nop 1
	v_addc_co_u32_e32 v155, vcc, 0, v57, vcc
	v_add_co_u32_e32 v158, vcc, s79, v56
	s_nop 1
	v_addc_co_u32_e32 v159, vcc, 0, v57, vcc
	v_add_co_u32_e32 v162, vcc, s80, v56
	s_nop 1
	v_addc_co_u32_e32 v163, vcc, 0, v57, vcc
	v_add_co_u32_e32 v166, vcc, s81, v56
	s_nop 1
	v_addc_co_u32_e32 v167, vcc, 0, v57, vcc
	v_add_co_u32_e32 v168, vcc, s82, v56
	s_nop 1
	v_addc_co_u32_e32 v169, vcc, 0, v57, vcc
	v_add_co_u32_e32 v170, vcc, s83, v56
	s_nop 1
	v_addc_co_u32_e32 v171, vcc, 0, v57, vcc
	v_add_co_u32_e32 v172, vcc, s84, v56
	s_nop 1
	v_addc_co_u32_e32 v173, vcc, 0, v57, vcc
	global_load_dwordx4 v[122:125], v[4:5], off offset:2048 nt
	global_load_dwordx4 v[130:133], v[6:7], off offset:1024 nt
	global_load_dwordx4 v[134:137], v[8:9], off nt
	global_load_dwordx4 v[138:141], v[10:11], off offset:3072 nt
	global_load_dwordx4 v[142:145], v[12:13], off offset:2048 nt
	global_load_dwordx4 v[146:149], v[14:15], off offset:1024 nt
	global_load_dwordx4 v[150:153], v[126:127], off nt
	s_nop 0
	global_load_dwordx4 v[154:157], v[154:155], off offset:3072 nt
	s_nop 0
	global_load_dwordx4 v[158:161], v[158:159], off offset:2048 nt
	s_nop 0
	global_load_dwordx4 v[162:165], v[162:163], off offset:1024 nt
	s_nop 0
	global_load_dwordx4 v[8:11], v[166:167], off nt
	global_load_dwordx4 v[12:15], v[168:169], off offset:3072 nt
	global_load_dwordx4 v[0:3], v[170:171], off offset:2048 nt
	global_load_dwordx4 v[4:7], v[172:173], off offset:1024 nt
	s_waitcnt vmcnt(14)
	v_max3_f32 v101, v93, |v114|, |v118|
	v_max3_f32 v97, v97, |v116|, |v120|
	v_max3_f32 v102, v94, |v115|, |v119|
	v_max3_f32 v98, v98, |v117|, |v121|
	v_cvt_pk_bf16_f32 v115, v114, v115
	v_cvt_pk_bf16_f32 v93, v116, v117
	v_cvt_pk_bf16_f32 v116, v118, v119
	v_cvt_pk_bf16_f32 v94, v120, v121
	s_waitcnt vmcnt(13)
	v_cvt_pk_bf16_f32 v117, v122, v123
	s_waitcnt vmcnt(12)
	v_max3_f32 v101, v101, |v122|, |v130|
	v_max3_f32 v105, v97, |v124|, |v132|
	v_max3_f32 v102, v102, |v123|, |v131|
	v_max3_f32 v106, v98, |v125|, |v133|
	s_waitcnt vmcnt(10)
	v_max3_f32 v109, v101, |v134|, |v138|
	v_max3_f32 v105, v105, |v136|, |v140|
	v_max3_f32 v110, v102, |v135|, |v139|
	v_max3_f32 v106, v106, |v137|, |v141|
	s_waitcnt vmcnt(8)
	v_max3_f32 v109, v109, |v142|, |v146|
	v_max3_f32 v113, v105, |v144|, |v148|
	v_cvt_pk_bf16_f32 v97, v124, v125
	v_max3_f32 v110, v110, |v143|, |v147|
	v_max3_f32 v114, v106, |v145|, |v149|
	s_waitcnt vmcnt(6)
	v_max3_f32 v125, v109, |v150|, |v154|
	v_max3_f32 v113, v113, |v152|, |v156|
	v_cvt_pk_bf16_f32 v118, v130, v131
	v_max3_f32 v126, v110, |v151|, |v155|
	v_max3_f32 v114, v114, |v153|, |v157|
	s_waitcnt vmcnt(4)
	v_max3_f32 v127, v125, |v158|, |v162|
	v_max3_f32 v130, v113, |v160|, |v164|
	v_cvt_pk_bf16_f32 v98, v132, v133
	v_max3_f32 v129, v126, |v159|, |v163|
	v_max3_f32 v131, v114, |v161|, |v165|
	s_waitcnt vmcnt(2)
	v_max3_f32 v132, v127, |v8|, |v12|
	v_max3_f32 v130, v130, |v10|, |v14|
	v_cvt_pk_bf16_f32 v119, v134, v135
	v_cvt_pk_bf16_f32 v101, v136, v137
	v_cvt_pk_bf16_f32 v120, v138, v139
	v_cvt_pk_bf16_f32 v102, v140, v141
	v_cvt_pk_bf16_f32 v121, v142, v143
	v_cvt_pk_bf16_f32 v105, v144, v145
	v_cvt_pk_bf16_f32 v122, v146, v147
	v_cvt_pk_bf16_f32 v106, v148, v149
	v_cvt_pk_bf16_f32 v123, v150, v151
	v_cvt_pk_bf16_f32 v109, v152, v153
	v_cvt_pk_bf16_f32 v124, v154, v155
	v_cvt_pk_bf16_f32 v110, v156, v157
	v_cvt_pk_bf16_f32 v125, v158, v159
	v_cvt_pk_bf16_f32 v113, v160, v161
	v_cvt_pk_bf16_f32 v126, v162, v163
	v_cvt_pk_bf16_f32 v114, v164, v165
	v_max3_f32 v133, v129, |v9|, |v13|
	v_max3_f32 v131, v131, |v11|, |v15|
	v_cvt_pk_bf16_f32 v127, v8, v9
	v_cvt_pk_bf16_f32 v8, v10, v11
	v_cvt_pk_bf16_f32 v129, v12, v13
	v_cvt_pk_bf16_f32 v9, v14, v15
	s_waitcnt vmcnt(0)
	v_max3_f32 v11, v132, |v0|, |v4|
	v_max3_f32 v135, v130, |v2|, |v6|
	v_cvt_pk_bf16_f32 v130, v0, v1
	v_add_co_u32_e32 v0, vcc, s42, v56
	v_max3_f32 v134, v133, |v1|, |v5|
	s_nop 0
	v_addc_co_u32_e32 v1, vcc, 0, v57, vcc
	v_max3_f32 v142, v131, |v3|, |v7|
	v_cvt_pk_bf16_f32 v10, v2, v3
	v_cvt_pk_bf16_f32 v131, v4, v5
	v_cvt_pk_bf16_f32 v4, v6, v7
	v_add_co_u32_e32 v6, vcc, s85, v56
	s_nop 1
	v_addc_co_u32_e32 v7, vcc, 0, v57, vcc
	global_load_dwordx4 v[0:3], v[0:1], off nt
	s_nop 0
	global_load_dwordx4 v[12:15], v[6:7], off offset:3072 nt
	v_add_co_u32_e32 v132, vcc, s86, v56
	v_addc_co_u32_e32 v133, vcc, 0, v57, vcc
	v_add_co_u32_e32 v136, vcc, s87, v56
	s_nop 0
	v_addc_co_u32_e32 v137, vcc, 0, v57, vcc
	v_add_co_u32_e32 v138, vcc, s88, v56
	s_nop 0
	v_addc_co_u32_e32 v139, vcc, 0, v57, vcc
	v_add_co_u32_e32 v140, vcc, s89, v56
	s_nop 0
	v_addc_co_u32_e32 v141, vcc, 0, v57, vcc
	v_add_co_u32_e32 v154, vcc, s90, v56
	s_nop 1
	v_addc_co_u32_e32 v155, vcc, 0, v57, vcc
	v_add_co_u32_e32 v158, vcc, s91, v56
	s_nop 1
	v_addc_co_u32_e32 v159, vcc, 0, v57, vcc
	v_add_co_u32_e32 v162, vcc, s92, v56
	s_nop 1
	v_addc_co_u32_e32 v163, vcc, 0, v57, vcc
	v_add_co_u32_e32 v166, vcc, s93, v56
	s_nop 1
	v_addc_co_u32_e32 v167, vcc, 0, v57, vcc
	v_add_co_u32_e32 v170, vcc, s94, v56
	s_nop 1
	v_addc_co_u32_e32 v171, vcc, 0, v57, vcc
	v_add_co_u32_e32 v174, vcc, s95, v56
	s_nop 1
	v_addc_co_u32_e32 v175, vcc, 0, v57, vcc
	v_add_co_u32_e32 v178, vcc, s96, v56
	s_nop 1
	v_addc_co_u32_e32 v179, vcc, 0, v57, vcc
	v_add_co_u32_e32 v182, vcc, s97, v56
	s_nop 1
	v_addc_co_u32_e32 v183, vcc, 0, v57, vcc
	v_add_co_u32_e32 v186, vcc, s34, v56
	s_nop 1
	v_addc_co_u32_e32 v187, vcc, 0, v57, vcc
	v_add_co_u32_e32 v56, vcc, s35, v56
	s_nop 1
	v_addc_co_u32_e32 v57, vcc, 0, v57, vcc
	v_mov_b32_e32 v206, v134
	v_mov_b32_e32 v207, v135
	v_mov_b32_e32 v208, v142
	global_load_dwordx4 v[132:135], v[132:133], off offset:2048 nt
	s_nop 0
	global_load_dwordx4 v[142:145], v[136:137], off offset:1024 nt
	global_load_dwordx4 v[146:149], v[138:139], off nt
	global_load_dwordx4 v[150:153], v[140:141], off offset:3072 nt
	s_nop 0
	global_load_dwordx4 v[154:157], v[154:155], off offset:2048 nt
	s_nop 0
	global_load_dwordx4 v[158:161], v[158:159], off offset:1024 nt
	s_nop 0
	global_load_dwordx4 v[162:165], v[162:163], off nt
	s_nop 0
	global_load_dwordx4 v[166:169], v[166:167], off offset:3072 nt
	s_nop 0
	global_load_dwordx4 v[170:173], v[170:171], off offset:2048 nt
	s_nop 0
	global_load_dwordx4 v[174:177], v[174:175], off offset:1024 nt
	s_nop 0
	global_load_dwordx4 v[178:181], v[178:179], off nt
	s_nop 0
	global_load_dwordx4 v[182:185], v[182:183], off offset:3072 nt
	s_nop 0
	global_load_dwordx4 v[186:189], v[186:187], off offset:2048 nt
	s_nop 0
	global_load_dwordx4 v[190:193], v[56:57], off offset:1024 nt
	s_waitcnt vmcnt(14)
	v_max3_f32 v7, v11, |v0|, |v12|
	v_max3_f32 v11, v206, |v1|, |v13|
	v_max3_f32 v194, v207, |v2|, |v14|
	v_max3_f32 v195, v208, |v3|, |v15|
	v_cvt_pk_bf16_f32 v138, v0, v1
	v_cvt_pk_bf16_f32 v5, v2, v3
	v_cvt_pk_bf16_f32 v139, v12, v13
	v_cvt_pk_bf16_f32 v6, v14, v15
	s_waitcnt vmcnt(13)
	v_cvt_pk_bf16_f32 v140, v132, v133
	s_waitcnt vmcnt(12)
	v_max3_f32 v0, v7, |v132|, |v142|
	v_max3_f32 v1, v11, |v133|, |v143|
	s_waitcnt vmcnt(10)
	v_max3_f32 v0, v0, |v146|, |v150|
	v_max3_f32 v2, v194, |v134|, |v144|
	s_waitcnt vmcnt(8)
	v_max3_f32 v0, v0, |v154|, |v158|
	v_cvt_pk_bf16_f32 v7, v134, v135
	s_waitcnt vmcnt(6)
	v_max3_f32 v0, v0, |v162|, |v166|
	v_cvt_pk_bf16_f32 v141, v142, v143
	s_waitcnt vmcnt(4)
	v_max3_f32 v0, v0, |v170|, |v174|
	v_cvt_pk_bf16_f32 v12, v144, v145
	s_waitcnt vmcnt(2)
	v_max3_f32 v0, v0, |v178|, |v182|
	v_max3_f32 v1, v1, |v147|, |v151|
	s_waitcnt vmcnt(0)
	v_max3_f32 v0, v0, |v186|, |v190|
	v_cvt_pk_bf16_f32 v142, v146, v147
	v_cvt_pk_bf16_f32 v11, v148, v149
	v_cvt_pk_bf16_f32 v143, v150, v151
	v_cvt_pk_bf16_f32 v13, v152, v153
	v_cvt_pk_bf16_f32 v144, v154, v155
	ds_swizzle_b32 v154, v0 offset:swizzle(SWAP,8)
	v_max3_f32 v1, v1, |v155|, |v159|
	v_max3_f32 v1, v1, |v163|, |v167|
	v_max3_f32 v1, v1, |v171|, |v175|
	v_max3_f32 v1, v1, |v179|, |v183|
	v_max3_f32 v1, v1, |v187|, |v191|
	s_waitcnt lgkmcnt(0)
	v_max_f32_e32 v154, v154, v154
	v_max3_f32 v2, v2, |v148|, |v152|
	v_max_f32_e32 v0, v0, v154
	ds_swizzle_b32 v154, v1 offset:swizzle(SWAP,8)
	v_max3_f32 v2, v2, |v156|, |v160|
	v_max3_f32 v2, v2, |v164|, |v168|
	v_max3_f32 v2, v2, |v172|, |v176|
	v_max3_f32 v2, v2, |v180|, |v184|
	v_max3_f32 v3, v195, |v135|, |v145|
	v_max3_f32 v2, v2, |v188|, |v192|
	s_waitcnt lgkmcnt(0)
	v_max_f32_e32 v154, v154, v154
	v_max3_f32 v3, v3, |v149|, |v153|
	v_max_f32_e32 v1, v1, v154
	ds_swizzle_b32 v154, v2 offset:swizzle(SWAP,8)
	v_max3_f32 v3, v3, |v157|, |v161|
	v_max3_f32 v3, v3, |v165|, |v169|
	v_max3_f32 v3, v3, |v173|, |v177|
	v_max3_f32 v3, v3, |v181|, |v185|
	v_max3_f32 v3, v3, |v189|, |v193|
	s_waitcnt lgkmcnt(0)
	v_max_f32_e32 v154, v154, v154
	v_max_f32_e32 v2, v2, v154
	ds_swizzle_b32 v154, v3 offset:swizzle(SWAP,8)
	v_cvt_pk_bf16_f32 v14, v156, v157
	v_cvt_pk_bf16_f32 v145, v158, v159
	v_cvt_pk_bf16_f32 v56, v160, v161
	v_cvt_pk_bf16_f32 v146, v162, v163
	s_waitcnt lgkmcnt(0)
	v_max_f32_e32 v154, v154, v154
	v_max_f32_e32 v3, v3, v154
	ds_swizzle_b32 v154, v0 offset:swizzle(SWAP,16)
	v_cvt_pk_bf16_f32 v15, v164, v165
	v_cvt_pk_bf16_f32 v147, v166, v167
	v_cvt_pk_bf16_f32 v57, v168, v169
	v_cvt_pk_bf16_f32 v148, v170, v171
	s_waitcnt lgkmcnt(0)
	v_max_f32_e32 v154, v154, v154
	v_max_f32_e32 v0, v0, v154
	ds_swizzle_b32 v154, v1 offset:swizzle(SWAP,16)
	v_cvt_pk_bf16_f32 v132, v172, v173
	v_cvt_pk_bf16_f32 v149, v174, v175
	v_cvt_pk_bf16_f32 v134, v176, v177
	v_cvt_pk_bf16_f32 v150, v178, v179
	s_waitcnt lgkmcnt(0)
	v_max_f32_e32 v154, v154, v154
	v_max_f32_e32 v1, v1, v154
	ds_swizzle_b32 v154, v2 offset:swizzle(SWAP,16)
	v_mov_b32_e32 v155, v1
	s_nop 1
	v_permlane32_swap_b32_e32 v1, v155
	v_cvt_pk_bf16_f32 v133, v180, v181
	s_waitcnt lgkmcnt(0)
	v_max_f32_e32 v154, v154, v154
	v_max_f32_e32 v2, v2, v154
	ds_swizzle_b32 v154, v3 offset:swizzle(SWAP,16)
	v_mov_b32_e32 v156, v2
	s_nop 1
	v_permlane32_swap_b32_e32 v2, v156
	v_cvt_pk_bf16_f32 v151, v182, v183
	s_waitcnt lgkmcnt(0)
	v_max_f32_e32 v154, v154, v154
	v_max_f32_e32 v3, v3, v154
	v_mov_b32_e32 v154, v0
	v_mov_b32_e32 v157, v3
	s_nop 0
	v_permlane32_swap_b32_e32 v0, v154
	v_permlane32_swap_b32_e32 v3, v157
	v_cvt_pk_bf16_f32 v135, v184, v185
	v_cvt_pk_bf16_f32 v152, v186, v187
	v_cvt_pk_bf16_f32 v136, v188, v189
	v_cvt_pk_bf16_f32 v153, v190, v191
	v_cvt_pk_bf16_f32 v137, v192, v193
	s_and_saveexec_b64 s[36:37], s[4:5]
	s_cbranch_execz .LBB0_31
	v_max_f32_e32 v0, v0, v0
	v_max_f32_e32 v154, v154, v154
	v_max_f32_e32 v0, v0, v154
	v_max_f32_e32 v1, v1, v1
	v_max_f32_e32 v154, v155, v155
	v_max_f32_e32 v1, v1, v154
	v_max_f32_e32 v2, v2, v2
	v_max_f32_e32 v154, v156, v156
	v_max_f32_e32 v2, v2, v154
	v_max_f32_e32 v3, v3, v3
	v_max_f32_e32 v154, v157, v157
	v_max_f32_e32 v3, v3, v154
	ds_write_b128 v85, v[0:3]
